# hgrn V^T LDS staging XOR-swizzled on 16B column blocks (removes 16-way ds_write_b16 bank conflicts)
# speedup vs baseline: 1.0085x; 1.0085x over previous
; __device__ __forceinline__ void item_hgrn(const Params& p, int l, int sidx) {
;     ...
;   const float* hg = p.hg_g + l * 128;
;   const int c = tid & 127, qd = wid >> 1;
;   float hgv[4];
; #pragma unroll
;   for (int n = 0; n < 4; ++n) hgv[n] = hg[(wid >> 2) * 64 + n * 16 + fr];
;   float lf[16]; unsigned qraw[16]; uint4 vraw[2];
.LBB0_800:
	s_ashr_i32 s0, s2, 2
	s_ashr_i32 s3, s2, 7
	s_and_b32 s10, s0, 0xffffffc0
	s_add_i32 s85, s86, -1
	s_lshl_b32 s0, s3, 4
	s_min_i32 s1, s0, s85
	s_add_i32 s4, s1, s91
	v_and_b32_e32 v117, 0x7f, v94
	s_ashr_i32 s5, s4, 31
	s_mov_b32 s54, 1
	s_mov_b32 s1, s0
	v_lshl_or_b32 v74, s84, 7, v117
	s_lshl_b64 s[4:5], s[4:5], 9
	s_or_b64 s[62:63], s[0:1], s[54:55]
	v_or_b32_e32 v0, s4, v74
	s_min_i32 s4, s62, s85
	s_add_i32 s4, s4, s91
	v_mov_b32_e32 v1, s5
	s_ashr_i32 s5, s4, 31
	s_lshl_b64 s[4:5], s[4:5], 9
	s_or_b32 s81, s0, 2
	v_or_b32_e32 v2, s4, v74
	s_min_i32 s4, s81, s85
	s_add_i32 s4, s4, s91
	v_mov_b32_e32 v3, s5
	s_ashr_i32 s5, s4, 31
	s_lshl_b64 s[4:5], s[4:5], 9
	v_or_b32_e32 v4, s4, v74
	s_min_i32 s4, s63, s85
	s_add_i32 s4, s4, s91
	v_mov_b32_e32 v5, s5
	s_ashr_i32 s5, s4, 31
	s_lshl_b64 s[4:5], s[4:5], 9
	v_or_b32_e32 v6, s4, v74
	v_mov_b32_e32 v7, s5
	s_mov_b32 s4, 4
	s_mov_b32 s5, 6
	s_or_b64 s[64:65], s[0:1], s[4:5]
	s_min_i32 s4, s64, s85
	s_add_i32 s4, s4, s91
	s_ashr_i32 s5, s4, 31
	s_lshl_b64 s[4:5], s[4:5], 9
	v_or_b32_e32 v20, s4, v74
	v_mov_b32_e32 v21, s5
	s_mov_b32 s4, 5
	s_mov_b32 s5, 7
	s_or_b64 s[66:67], s[0:1], s[4:5]
	s_min_i32 s4, s66, s85
	s_add_i32 s4, s4, s91
	s_ashr_i32 s5, s4, 31
	s_lshl_b64 s[4:5], s[4:5], 9
	v_or_b32_e32 v36, s4, v74
	s_min_i32 s4, s65, s85
	s_add_i32 s4, s4, s91
	v_mov_b32_e32 v37, s5
	s_ashr_i32 s5, s4, 31
	s_lshl_b64 s[4:5], s[4:5], 9
	v_or_b32_e32 v46, s4, v74
	s_min_i32 s4, s67, s85
	s_add_i32 s4, s4, s91
	v_mov_b32_e32 v47, s5
	s_ashr_i32 s5, s4, 31
	s_lshl_b64 s[4:5], s[4:5], 9
	v_or_b32_e32 v48, s4, v74
	v_mov_b32_e32 v49, s5
	s_mov_b32 s4, 8
	s_mov_b32 s5, 10
	s_or_b64 s[68:69], s[0:1], s[4:5]
	s_min_i32 s4, s68, s85
	s_add_i32 s4, s4, s91
	s_ashr_i32 s5, s4, 31
	s_lshl_b64 s[4:5], s[4:5], 9
	v_or_b32_e32 v50, s4, v74
	v_mov_b32_e32 v51, s5
	s_mov_b32 s4, 9
	s_mov_b32 s5, 11
	s_or_b64 s[70:71], s[0:1], s[4:5]
	s_min_i32 s4, s70, s85
	s_add_i32 s4, s4, s91
	s_ashr_i32 s5, s4, 31
	s_lshl_b64 s[4:5], s[4:5], 9
	v_or_b32_e32 v52, s4, v74
	s_min_i32 s4, s69, s85
	s_add_i32 s4, s4, s91
	v_mov_b32_e32 v53, s5
	s_ashr_i32 s5, s4, 31
	s_lshl_b64 s[4:5], s[4:5], 9
	v_or_b32_e32 v54, s4, v74
	s_min_i32 s4, s71, s85
	s_add_i32 s4, s4, s91
	v_mov_b32_e32 v55, s5
	s_ashr_i32 s5, s4, 31
	s_lshl_b64 s[4:5], s[4:5], 9
	v_or_b32_e32 v56, s4, v74
	v_mov_b32_e32 v57, s5
	s_mov_b32 s4, 12
	s_mov_b32 s5, 14
	s_or_b64 s[72:73], s[0:1], s[4:5]
	s_min_i32 s4, s72, s85
	s_add_i32 s4, s4, s91
	s_ashr_i32 s5, s4, 31
	s_lshl_b64 s[4:5], s[4:5], 9
	v_or_b32_e32 v58, s4, v74
	v_mov_b32_e32 v59, s5
	s_mov_b32 s4, 13
	s_mov_b32 s5, 15
	s_or_b64 s[74:75], s[0:1], s[4:5]
	s_min_i32 s1, s74, s85
	s_add_i32 s4, s1, s91
	s_ashr_i32 s5, s4, 31
	s_lshl_b64 s[4:5], s[4:5], 9
	s_min_i32 s1, s73, s85
	v_or_b32_e32 v82, s4, v74
	s_add_i32 s4, s1, s91
	v_mov_b32_e32 v83, s5
	s_ashr_i32 s5, s4, 31
	s_lshl_b64 s[4:5], s[4:5], 9
	s_min_i32 s1, s75, s85
	v_or_b32_e32 v84, s4, v74
	s_add_i32 s4, s1, s91
	v_mov_b32_e32 v85, s5
	s_ashr_i32 s5, s4, 31
	v_readlane_b32 s16, v248, 49
	s_lshl_b64 s[4:5], s[4:5], 9
	s_lshl_b32 s14, s84, 8
	v_readlane_b32 s28, v248, 61
	v_or_b32_e32 v86, s4, v74
	v_readlane_b32 s29, v248, 62
	s_add_u32 s4, s28, s14
	v_mov_b32_e32 v87, s5
	v_readlane_b32 s19, v248, 52
	s_addc_u32 s5, s29, 0
	s_and_b32 s1, s2, 0x3fffff80
	s_lshl_b32 s1, s1, 2
	v_readlane_b32 s19, v247, 36
	s_add_i32 s16, s19, s1
	v_lshlrev_b32_e32 v22, 3, v94
	s_cmpk_lt_u32 s2, 0x80
	v_and_b32_e32 v119, 0x78, v22
	s_cselect_b64 s[76:77], -1, 0
	s_cmp_eq_u32 s3, 1
	v_readlane_b32 s17, v248, 50
	v_readlane_b32 s20, v248, 53
	v_readlane_b32 s21, v248, 54
	v_lshlrev_b32_e32 v190, 1, v119
	s_cselect_b64 s[6:7], -1, 0
	s_lshl_b32 s1, s3, 5
	v_readlane_b32 s18, v248, 51
	v_lshl_add_u64 v[76:77], s[4:5], 0, v[190:191]
	s_add_i32 s17, s1, 0x100
	s_bfe_u32 s4, s2, 0x20006
	s_and_b32 s5, s2, 0xffffffc0
	s_lshl_b32 s1, s12, 5
	v_readlane_b32 s21, v247, 38
	v_readlane_b32 s20, v247, 37
	s_lshl_b32 s13, s4, 4
	s_ashr_i32 s11, s10, 31
	s_add_i32 s18, s21, s1
	s_add_i32 s1, s20, s5
	s_cmp_eq_u32 s3, 2
	s_cselect_b64 s[8:9], -1, 0
	v_writelane_b32 v246, s8, 38
	v_or_b32_e32 v22, s10, v61
	v_readlane_b32 s36, v247, 7
	v_writelane_b32 v246, s9, 39
	v_ashrrev_i32_e32 v23, 31, v22
	v_readlane_b32 s8, v246, 27
	v_readlane_b32 s9, v246, 28
	v_readlane_b32 s37, v247, 8
	v_readlane_b32 s44, v247, 15
	v_readlane_b32 s45, v247, 16
	v_lshl_add_u64 v[88:89], v[22:23], 2, s[8:9]
	global_load_dword v69, v[88:89], off
	global_load_dword v71, v[88:89], off offset:64
	global_load_dword v73, v[88:89], off offset:128
	global_load_dword v75, v[88:89], off offset:192
	v_lshl_add_u64 v[88:89], v[0:1], 2, s[44:45]
	v_lshl_add_u64 v[0:1], v[0:1], 1, s[36:37]
	global_load_dword v88, v[88:89], off
	v_readlane_b32 s22, v248, 55
	global_load_ushort v89, v[0:1], off
	v_lshl_add_u64 v[0:1], v[2:3], 2, s[44:45]
	global_load_dword v90, v[0:1], off
	v_lshl_add_u64 v[0:1], v[2:3], 1, s[36:37]
	global_load_ushort v91, v[0:1], off
	v_lshl_add_u64 v[0:1], v[4:5], 2, s[44:45]
	global_load_dword v92, v[0:1], off
	v_lshl_add_u64 v[0:1], v[4:5], 1, s[36:37]
	global_load_ushort v93, v[0:1], off
	v_lshl_add_u64 v[0:1], v[6:7], 2, s[44:45]
	global_load_dword v98, v[0:1], off
	v_lshl_add_u64 v[0:1], v[6:7], 1, s[36:37]
	global_load_ushort v100, v[0:1], off
	v_lshl_add_u64 v[0:1], v[20:21], 2, s[44:45]
	global_load_dword v102, v[0:1], off
	v_lshl_add_u64 v[0:1], v[20:21], 1, s[36:37]
	global_load_ushort v103, v[0:1], off
	v_lshl_add_u64 v[0:1], v[36:37], 2, s[44:45]
	global_load_dword v104, v[0:1], off
	v_lshl_add_u64 v[0:1], v[36:37], 1, s[36:37]
	global_load_ushort v105, v[0:1], off
	v_lshl_add_u64 v[0:1], v[46:47], 2, s[44:45]
	global_load_dword v106, v[0:1], off
	v_lshl_add_u64 v[0:1], v[46:47], 1, s[36:37]
	global_load_ushort v107, v[0:1], off
	v_lshl_add_u64 v[0:1], v[48:49], 2, s[44:45]
	global_load_dword v108, v[0:1], off
	v_lshl_add_u64 v[0:1], v[48:49], 1, s[36:37]
	global_load_ushort v109, v[0:1], off
	v_lshl_add_u64 v[0:1], v[50:51], 2, s[44:45]
	global_load_dword v110, v[0:1], off
	v_lshl_add_u64 v[0:1], v[50:51], 1, s[36:37]
	global_load_ushort v111, v[0:1], off
	v_lshl_add_u64 v[0:1], v[52:53], 2, s[44:45]
	global_load_dword v112, v[0:1], off
	v_lshl_add_u64 v[0:1], v[52:53], 1, s[36:37]
	global_load_ushort v113, v[0:1], off
	v_lshl_add_u64 v[0:1], v[54:55], 2, s[44:45]
	global_load_dword v114, v[0:1], off
	v_lshl_add_u64 v[0:1], v[54:55], 1, s[36:37]
	global_load_ushort v115, v[0:1], off
	v_lshl_add_u64 v[0:1], v[56:57], 2, s[44:45]
	global_load_dword v116, v[0:1], off
	v_lshl_add_u64 v[0:1], v[56:57], 1, s[36:37]
	global_load_ushort v118, v[0:1], off
	v_lshl_add_u64 v[0:1], v[58:59], 2, s[44:45]
	global_load_dword v133, v[0:1], off
	v_lshl_add_u64 v[0:1], v[58:59], 1, s[36:37]
	global_load_ushort v138, v[0:1], off
	v_lshl_add_u64 v[0:1], v[82:83], 2, s[44:45]
	global_load_dword v139, v[0:1], off
	v_lshl_add_u64 v[0:1], v[82:83], 1, s[36:37]
	global_load_ushort v140, v[0:1], off
	v_lshl_add_u64 v[0:1], v[84:85], 2, s[44:45]
	global_load_dword v141, v[0:1], off
	v_lshl_add_u64 v[0:1], v[84:85], 1, s[36:37]
	global_load_ushort v142, v[0:1], off
	v_lshl_add_u64 v[0:1], v[86:87], 2, s[44:45]
	v_add_u32_e32 v2, 0x200, v94
	global_load_dword v143, v[0:1], off
	v_lshl_add_u64 v[0:1], v[86:87], 1, s[36:37]
	v_ashrrev_i32_e32 v86, 4, v94
	v_ashrrev_i32_e32 v87, 4, v2
	global_load_ushort v144, v[0:1], off
	v_min_i32_e32 v0, s85, v86
	v_min_i32_e32 v2, s85, v87
	v_add_u32_e32 v0, s91, v0
	v_add_u32_e32 v2, s91, v2
	v_ashrrev_i32_e32 v1, 31, v0
	v_ashrrev_i32_e32 v3, 31, v2
	v_lshlrev_b64 v[0:1], 10, v[0:1]
	v_lshlrev_b64 v[2:3], 10, v[2:3]
	v_lshl_add_u64 v[0:1], v[76:77], 0, v[0:1]
	v_lshl_add_u64 v[4:5], v[76:77], 0, v[2:3]
	global_load_dwordx4 v[0:3], v[0:1], off
	s_nop 0
	global_load_dwordx4 v[4:7], v[4:5], off
	s_and_b32 s2, s2, 0xffffff00
	v_readlane_b32 s22, v247, 41
	s_add_i32 s87, s22, s2
	s_lshl_b32 s2, s4, 6
	s_add_i32 s87, s87, s2
	s_lshl_b32 s2, s12, 1
	v_readlane_b32 s12, v247, 39
	s_and_b32 s2, s2, 2
	s_add_i32 s88, s12, s5
	s_cmp_le_i32 s2, s3
	s_cselect_b64 s[78:79], -1, 0
	s_cmp_lt_i32 s2, s3
	v_readlane_b32 s38, v247, 9
	s_cselect_b64 s[4:5], -1, 0
	v_readlane_b32 s39, v247, 10
	s_add_u32 s14, s38, s14
	s_addc_u32 s15, s39, 0
	s_lshl_b64 s[10:11], s[10:11], 1
	s_add_u32 s10, s14, s10
	v_lshl_add_u32 v164, v96, 3, s18
	v_lshlrev_b32_e32 v96, 4, v96
	s_addc_u32 s11, s15, s11
	v_lshlrev_b32_e32 v190, 1, v61
	v_lshl_add_u64 v[80:81], v[22:23], 1, s[14:15]
	v_or_b32_e32 v21, s13, v63
	v_or_b32_e32 v36, s0, v61
	v_add_u32_e32 v20, 0x100, v96
	s_movk_i32 s15, 0x110
	v_lshl_add_u64 v[78:79], s[10:11], 0, v[190:191]
	v_lshlrev_b32_e32 v99, 2, v117
	v_mad_u64_u32 v[82:83], s[10:11], v36, s15, v[20:21]
	v_or_b32_e32 v36, s13, v61
	v_add_u32_e32 v67, s16, v99
	v_add_u32_e32 v94, s19, v99
	v_add_u32_e32 v97, s20, v99
	v_add_u32_e32 v99, s12, v99
	v_mul_u32_u24_e32 v37, 0x90, v36
	v_readlane_b32 s12, v247, 40
	s_mulk_i32 s3, 0x880
	s_movk_i32 s14, 0x90
	v_add3_u32 v83, s12, v37, v96
	v_or_b32_e32 v37, s3, v117
	s_mul_i32 s3, s62, 0x88
	v_add_u32_e32 v46, s3, v117
	s_mul_i32 s3, s81, 0x88
	v_add_u32_e32 v47, s3, v117
	s_mul_i32 s3, s63, 0x88
	v_add_u32_e32 v48, s3, v117
	s_mul_i32 s3, s64, 0x88
	v_add_u32_e32 v49, s3, v117
	s_mul_i32 s3, s66, 0x88
	v_add_u32_e32 v50, s3, v117
	s_mul_i32 s3, s65, 0x88
	v_add_u32_e32 v51, s3, v117
	s_mul_i32 s3, s67, 0x88
	v_add_u32_e32 v52, s3, v117
	s_mul_i32 s3, s68, 0x88
	v_add_u32_e32 v53, s3, v117
	s_mul_i32 s3, s70, 0x88
	v_add_u32_e32 v54, s3, v117
	s_mul_i32 s3, s69, 0x88
	v_add_u32_e32 v55, s3, v117
	s_mul_i32 s3, s71, 0x88
	v_add_u32_e32 v56, s3, v117
	s_mul_i32 s3, s72, 0x88
	v_add_u32_e32 v57, s3, v117
	s_mul_i32 s3, s74, 0x88
	v_or_b32_e32 v84, v65, v61
	v_add_u32_e32 v58, s3, v117
	s_mul_i32 s3, s73, 0x88
	v_mad_u64_u32 v[84:85], s[10:11], v84, s14, v[20:21]
	v_add_u32_e32 v59, s3, v117
	v_mul_u32_u24_e32 v85, 0x48, v119
	v_lshl_add_u32 v129, v53, 1, v216
	v_lshl_or_b32 v53, s2, 4, v61
	v_mov_b32_e32 v95, s17
	v_or_b32_e32 v23, s0, v63
	s_mul_i32 s3, s75, 0x88
	v_lshlrev_b32_e32 v119, 1, v85
	v_lshl_add_u32 v136, v59, 1, v216
	v_or_b32_e32 v59, 16, v53
	v_mad_u32_u24 v95, v117, s14, v95
; __device__ __forceinline__ void item_hgrn(const Params& p, int l, int sidx) {
;     ...
;         VTs[(dv0 + 2 * k) * 72 + s] = (u16)(w[k] & 0xffffu);
;         VTs[(dv0 + 2 * k + 1) * 72 + s] = (u16)(w[k] >> 16);
;     ...
;         for (int j = 0; j < 4; ++j) {
;           int trow = tt * 16 + fq * 4 + j, scol = st * 16 + fr;
;           float v = (scol <= trow) ? pa[j] : 0.f;
;           Ps[trow * 72 + scol] = f2bf(v);
;     ...
;           bf16x8 bb = *reinterpret_cast<const bf16x8*>(VTs + (dvh * 64 + n * 16 + fr) * 72 + ks * 32 + fq * 8);
;           oacc[n] = __builtin_amdgcn_mfma_f32_16x16x32_bf16(a, bb, oacc[n], 0, 0, 0);
;         }
;       }
; #pragma unroll
;       for (int ks = 0; ks < 4; ++ks) {
;         bf16x8 a = *reinterpret_cast<const bf16x8*>(Qs + (tt * 16 + fr) * 136 + ks * 32 + fq * 8);
; #pragma unroll
;         for (int n = 0; n < 4; ++n) {
;           bf16x8 bb = *reinterpret_cast<const bf16x8*>(SpT + (dvh * 64 + n * 16 + fr) * 136 + ks * 32 + fq * 8);
;           oacc[n] = __builtin_amdgcn_mfma_f32_16x16x32_bf16(a, bb, oacc[n], 0, 0, 0);
;         }
;       }
; #pragma unroll
;       for (int j = 0; j < 4; ++j) {
;         float ss = 0.f;
; #pragma unroll
;         for (int n = 0; n < 4; ++n) ss += oacc[n][j] * oacc[n][j];
;         ss += __shfl_xor(ss, 1); ss += __shfl_xor(ss, 2); ss += __shfl_xor(ss, 4); ss += __shfl_xor(ss, 8);
;         if (fr == 0) ssq[dvh * 64 + tt * 16 + fq * 4 + j] = ss;
;       }
;     }
;     {
; #pragma unroll
;       for (int ks = 0; ks < 2; ++ks) {
;         bf16x8 a = *reinterpret_cast<const bf16x8*>(KTs + (16 * wid + fr) * 72 + ks * 32 + fq * 8);
; #pragma unroll
;         for (int n = 0; n < 8; ++n) {
;           bf16x8 bb = *reinterpret_cast<const bf16x8*>(VTs + (n * 16 + fr) * 72 + ks * 32 + fq * 8);
	v_add_u32_e32 v137, s3, v117
	v_lshlrev_b32_e32 v117, 1, v86
	s_movk_i32 s3, 0x100
	v_add_u32_e32 v120, 0x100, v119
	v_lshlrev_b32_e32 v121, 1, v87
	v_lshl_add_u32 v131, v55, 1, v216
	v_mul_lo_u32 v55, v23, s14
	v_lshlrev_b32_e32 v149, 1, v59
	v_readlane_b32 s23, v248, 56
	v_readlane_b32 s24, v248, 57
	v_readlane_b32 s25, v248, 58
	v_readlane_b32 s26, v248, 59
	v_readlane_b32 s27, v248, 60
	v_mad_u32_u24 v101, v36, s15, v20
	v_add_u32_e32 v36, s21, v96
	v_add3_u32 v85, s3, v117, v119
	v_add_u32_e32 v117, v120, v117
	v_add3_u32 v119, s3, v121, v119
	v_add_u32_e32 v120, v120, v121
	v_lshl_add_u32 v121, v37, 1, v216
	v_lshl_add_u32 v122, v46, 1, v216
	v_lshl_add_u32 v123, v47, 1, v216
	v_lshl_add_u32 v124, v48, 1, v216
	v_lshl_add_u32 v125, v49, 1, v216
	v_lshl_add_u32 v126, v50, 1, v216
	v_lshl_add_u32 v127, v51, 1, v216
	v_lshl_add_u32 v128, v52, 1, v216
	v_lshl_add_u32 v130, v54, 1, v216
	v_lshl_add_u32 v132, v56, 1, v216
	v_lshl_add_u32 v134, v57, 1, v216
	v_lshl_add_u32 v135, v58, 1, v216
	v_mul_u32_u24_e32 v37, 0x110, v61
	v_mul_i32_i24_e32 v46, 0x110, v72
	v_mul_i32_i24_e32 v47, 0x110, v70
	v_mul_i32_i24_e32 v48, 0x110, v68
	v_mul_i32_i24_e32 v49, 0x110, v66
	v_mul_i32_i24_e32 v50, 0x110, v64
	v_mul_i32_i24_e32 v51, 0x110, v62
	v_mul_i32_i24_e32 v52, 0x110, v60
	v_mul_u32_u24_e32 v54, 0x110, v53
	v_or_b32_e32 v56, 1, v23
	v_or_b32_e32 v57, 2, v23
	v_or_b32_e32 v58, 3, v23
	v_mul_lo_u32 v166, v22, s14
	v_mul_lo_u32 v22, v22, s15
	v_mul_u32_u24_e32 v168, 0x90, v61
	v_mul_i32_i24_e32 v169, 0x90, v72
	v_mul_i32_i24_e32 v170, 0x90, v70
	v_mul_i32_i24_e32 v171, 0x90, v68
	v_mul_i32_i24_e32 v172, 0x90, v66
	v_mul_i32_i24_e32 v173, 0x90, v64
	v_mul_i32_i24_e32 v174, 0x90, v62
	v_mul_i32_i24_e32 v175, 0x90, v60
	v_lshl_add_u32 v145, v21, 2, s22
	v_lshl_add_u32 v21, v53, 1, s12
	v_add3_u32 v149, s12, v55, v149
	s_add_i32 s2, s91, s13
	s_mov_b32 s83, 0
	v_lshl_add_u32 v137, v137, 1, v216
	v_add_u32_e32 v146, 4, v145
	v_add_u32_e32 v147, 8, v145
	v_add_u32_e32 v148, 12, v145
	v_add_u32_e32 v150, 0x90, v149
	v_add_u32_e32 v151, 0x120, v149
	v_add_u32_e32 v152, 0x1b0, v149
	v_add_u32_e32 v153, 64, v87
	v_add_u32_e32 v154, 64, v86
	s_lshl_b32 s82, s95, 6
	v_add_u32_e32 v155, s13, v63
	v_add_u32_e32 v156, s2, v63
	v_add_u32_e32 v157, v164, v37
	v_add_u32_e32 v158, v164, v46
	v_add_u32_e32 v159, v164, v47
	v_add_u32_e32 v160, v164, v48
	v_add_u32_e32 v161, v164, v49
	v_add_u32_e32 v162, v164, v50
	v_add_u32_e32 v163, v164, v51
	v_add_u32_e32 v164, v164, v52
	v_add_u32_e32 v165, v21, v55
	v_add_u32_e32 v166, v20, v166
	v_add_u32_e32 v167, v36, v22
	v_add_u32_e32 v168, v20, v168
	v_add_u32_e32 v169, v20, v169
	v_add_u32_e32 v170, v20, v170
	v_add_u32_e32 v171, v20, v171
	v_add_u32_e32 v172, v20, v172
	v_add_u32_e32 v173, v20, v173
	v_add_u32_e32 v174, v20, v174
	v_add_u32_e32 v175, v20, v175
	v_and_b32_e32 v234, 8, v61
	v_lshlrev_b32_e32 v234, 1, v234
	v_xor_b32_e32 v235, v96, v234
	v_xor_b32_e32 v236, 32, v235
	v_sub_u32_e32 v235, v235, v96
	v_sub_u32_e32 v236, v236, v96
	v_add_u32_e32 v239, v166, v236
	v_add_u32_e32 v166, v166, v235
	v_add_u32_e32 v168, v168, v235
	v_add_u32_e32 v170, v170, v235
	v_add_u32_e32 v172, v172, v235
	v_add_u32_e32 v174, v174, v235
	v_add_u32_e32 v169, v169, v236
	v_add_u32_e32 v171, v171, v236
	v_add_u32_e32 v173, v173, v236
	v_add_u32_e32 v175, v175, v236
	v_lshrrev_b32_e32 v237, 7, v188
	v_and_b32_e32 v238, 7, v188
	v_xor_b32_e32 v234, v237, v238
	v_sub_u32_e32 v234, v234, v237
	v_lshlrev_b32_e32 v234, 4, v234
	v_add_u32_e32 v85, v85, v234
	v_add_u32_e32 v117, v117, v234
	v_or_b32_e32 v237, 4, v237
	v_xor_b32_e32 v234, v237, v238
	v_sub_u32_e32 v234, v234, v237
	v_lshlrev_b32_e32 v234, 4, v234
	v_add_u32_e32 v119, v119, v234
	v_add_u32_e32 v120, v120, v234
	v_add_u32_e32 v176, v20, v54
	s_mov_b32 s94, s86
	v_cmp_eq_u32_e64 s[10:11], 0, v61
	v_cmp_gt_i32_e64 s[12:13], v53, v23
	v_cmp_gt_i32_e64 s[14:15], v53, v56
	v_cmp_gt_i32_e64 s[16:17], v53, v57
	v_cmp_gt_i32_e64 s[18:19], v53, v58
	v_cmp_gt_i32_e64 s[20:21], v59, v23
	v_cmp_gt_i32_e64 s[22:23], v59, v56
	v_cmp_gt_i32_e64 s[24:25], v59, v57
	v_cmp_gt_i32_e64 s[26:27], v59, v58
	v_readlane_b32 s30, v248, 63
	v_readlane_b32 s31, v247, 0
	v_readlane_b32 s40, v247, 11
	v_readlane_b32 s41, v247, 12
	v_readlane_b32 s42, v247, 13
	v_readlane_b32 s43, v247, 14
	v_readlane_b32 s46, v247, 17
	v_readlane_b32 s47, v247, 18
	v_readlane_b32 s48, v247, 19
	v_readlane_b32 s49, v247, 20
	v_readlane_b32 s50, v247, 21
	v_readlane_b32 s51, v247, 22
	s_waitcnt vmcnt(0)
	s_branch .LBB0_802

; __device__ __forceinline__ void item_hgrn(const Params& p, int l, int sidx) {
;     ...
; #pragma unroll
;         for (int j = 0; j < 4; ++j) {
;           int trow = tt * 16 + fq * 4 + j, scol = st * 16 + fr;
;           float v = (scol <= trow) ? pa[j] : 0.f;
;           Ps[trow * 72 + scol] = f2bf(v);
;         }
;       }
;     }
;     __syncthreads();
;     f32x4 oacc[4];
;     const int tt = wid & 3, dvh = wid >> 2;
;     {
; #pragma unroll
;       for (int n = 0; n < 4; ++n) oacc[n] = f32x4{0.f, 0.f, 0.f, 0.f};
; #pragma unroll
;       for (int ks = 0; ks < 2; ++ks) {
;         bf16x8 a = *reinterpret_cast<const bf16x8*>(Ps + (tt * 16 + fr) * 72 + ks * 32 + fq * 8);
; #pragma unroll
;         for (int n = 0; n < 4; ++n) {
;           bf16x8 bb = *reinterpret_cast<const bf16x8*>(VTs + (dvh * 64 + n * 16 + fr) * 72 + ks * 32 + fq * 8);
;           oacc[n] = __builtin_amdgcn_mfma_f32_16x16x32_bf16(a, bb, oacc[n], 0, 0, 0);
;         }
;       }
; #pragma unroll
;       for (int ks = 0; ks < 4; ++ks) {
;         bf16x8 a = *reinterpret_cast<const bf16x8*>(Qs + (tt * 16 + fr) * 136 + ks * 32 + fq * 8);
; #pragma unroll
;         for (int n = 0; n < 4; ++n) {
;           bf16x8 bb = *reinterpret_cast<const bf16x8*>(SpT + (dvh * 64 + n * 16 + fr) * 136 + ks * 32 + fq * 8);
;           oacc[n] = __builtin_amdgcn_mfma_f32_16x16x32_bf16(a, bb, oacc[n], 0, 0, 0);
;         }
;       }
; #pragma unroll
;       for (int j = 0; j < 4; ++j) {
;         float ss = 0.f;
; #pragma unroll
;         for (int n = 0; n < 4; ++n) ss += oacc[n][j] * oacc[n][j];
;         ss += __shfl_xor(ss, 1); ss += __shfl_xor(ss, 2); ss += __shfl_xor(ss, 4); ss += __shfl_xor(ss, 8);
;         if (fr == 0) ssq[dvh * 64 + tt * 16 + fq * 4 + j] = ss;
;       }
.LBB0_816:
	s_nop 7
	v_cndmask_b32_e64 v40, v40, 0, s[20:21]
	v_bfe_u32 v44, v40, 16, 1
	v_add3_u32 v40, v40, v44, s80
	ds_write_b16_d16_hi v149, v40
	v_cndmask_b32_e64 v40, v41, 0, s[22:23]
	v_bfe_u32 v41, v40, 16, 1
	v_add3_u32 v40, v40, v41, s80
	ds_write_b16_d16_hi v150, v40
	v_cndmask_b32_e64 v40, v42, 0, s[24:25]
	v_bfe_u32 v41, v40, 16, 1
	v_add3_u32 v40, v40, v41, s80
	ds_write_b16_d16_hi v151, v40
	v_cndmask_b32_e64 v40, v43, 0, s[26:27]
	v_bfe_u32 v41, v40, 16, 1
	v_add3_u32 v40, v40, v41, s80
	ds_write_b16_d16_hi v152, v40
	s_waitcnt lgkmcnt(0)
	s_barrier
	ds_read_b128 v[40:43], v83
	ds_read_b128 v[44:47], v166 offset:53248
	ds_read_b128 v[48:51], v239 offset:55552
	ds_read_b128 v[52:55], v166 offset:57920
	ds_read_b128 v[56:59], v239 offset:60224
	s_waitcnt lgkmcnt(3)
	v_mfma_f32_16x16x32_bf16 v[44:47], v[40:43], v[44:47], 0
	v_xor_b32_e32 v207, 8, v215
	s_waitcnt lgkmcnt(2)
	v_mfma_f32_16x16x32_bf16 v[48:51], v[40:43], v[48:51], 0
	s_waitcnt lgkmcnt(1)
	v_mfma_f32_16x16x32_bf16 v[52:55], v[40:43], v[52:55], 0
	s_waitcnt lgkmcnt(0)
	v_mfma_f32_16x16x32_bf16 v[40:43], v[40:43], v[56:59], 0
	ds_read_b128 v[56:59], v83 offset:64
	ds_read_b128 v[218:221], v166 offset:53312
	s_waitcnt lgkmcnt(0)
	v_mfma_f32_16x16x32_bf16 v[44:47], v[56:59], v[218:221], v[44:47]
	ds_read_b128 v[218:221], v239 offset:55616
	s_waitcnt lgkmcnt(0)
	v_mfma_f32_16x16x32_bf16 v[48:51], v[56:59], v[218:221], v[48:51]
	ds_read_b128 v[218:221], v166 offset:57856
	s_waitcnt lgkmcnt(0)
	v_mfma_f32_16x16x32_bf16 v[52:55], v[56:59], v[218:221], v[52:55]
	ds_read_b128 v[218:221], v239 offset:60160
	s_waitcnt lgkmcnt(0)
	v_mfma_f32_16x16x32_bf16 v[40:43], v[56:59], v[218:221], v[40:43]
	ds_read_b128 v[56:59], v101
	ds_read_b128 v[218:221], v167
	s_waitcnt lgkmcnt(0)
	v_mfma_f32_16x16x32_bf16 v[44:47], v[56:59], v[218:221], v[44:47]
	ds_read_b128 v[218:221], v167 offset:4352
	s_waitcnt lgkmcnt(0)
	v_mfma_f32_16x16x32_bf16 v[48:51], v[56:59], v[218:221], v[48:51]
	ds_read_b128 v[218:221], v167 offset:8704
	s_waitcnt lgkmcnt(0)
	v_mfma_f32_16x16x32_bf16 v[52:55], v[56:59], v[218:221], v[52:55]
	ds_read_b128 v[218:221], v167 offset:13056
	s_waitcnt lgkmcnt(0)
	v_mfma_f32_16x16x32_bf16 v[40:43], v[56:59], v[218:221], v[40:43]
	ds_read_b128 v[56:59], v101 offset:64
	ds_read_b128 v[218:221], v167 offset:64
	s_waitcnt lgkmcnt(0)
	v_mfma_f32_16x16x32_bf16 v[44:47], v[56:59], v[218:221], v[44:47]
	ds_read_b128 v[218:221], v167 offset:4416
	s_waitcnt lgkmcnt(0)
	v_mfma_f32_16x16x32_bf16 v[48:51], v[56:59], v[218:221], v[48:51]
	ds_read_b128 v[218:221], v167 offset:8768
	s_waitcnt lgkmcnt(0)
	v_mfma_f32_16x16x32_bf16 v[52:55], v[56:59], v[218:221], v[52:55]
	ds_read_b128 v[218:221], v167 offset:13120
	s_waitcnt lgkmcnt(0)
	v_mfma_f32_16x16x32_bf16 v[40:43], v[56:59], v[218:221], v[40:43]
	ds_read_b128 v[56:59], v101 offset:128
	ds_read_b128 v[218:221], v167 offset:128
	s_waitcnt lgkmcnt(0)
	v_mfma_f32_16x16x32_bf16 v[44:47], v[56:59], v[218:221], v[44:47]
	ds_read_b128 v[218:221], v167 offset:4480
	s_waitcnt lgkmcnt(0)
	v_mfma_f32_16x16x32_bf16 v[48:51], v[56:59], v[218:221], v[48:51]
	ds_read_b128 v[218:221], v167 offset:8832
	s_waitcnt lgkmcnt(0)
	v_mfma_f32_16x16x32_bf16 v[52:55], v[56:59], v[218:221], v[52:55]
	ds_read_b128 v[218:221], v167 offset:13184
	s_waitcnt lgkmcnt(0)
	v_mfma_f32_16x16x32_bf16 v[56:59], v[56:59], v[218:221], v[40:43]
	ds_read_b128 v[218:221], v101 offset:192
	s_nop 1
	ds_read_b128 v[40:43], v167 offset:192
	s_waitcnt lgkmcnt(0)
	v_mfma_f32_16x16x32_bf16 v[40:43], v[218:221], v[40:43], v[44:47]
	s_nop 2
	ds_read_b128 v[44:47], v167 offset:4544
	s_waitcnt lgkmcnt(0)
	v_mfma_f32_16x16x32_bf16 v[44:47], v[218:221], v[44:47], v[48:51]
	s_nop 2
	ds_read_b128 v[48:51], v167 offset:8896
	s_waitcnt lgkmcnt(0)
	v_mfma_f32_16x16x32_bf16 v[48:51], v[218:221], v[48:51], v[52:55]
	s_nop 2
	ds_read_b128 v[52:55], v167 offset:13248
	s_waitcnt lgkmcnt(0)
	v_mfma_f32_16x16x32_bf16 v[52:55], v[218:221], v[52:55], v[56:59]
	s_nop 2
	v_and_b32_e32 v57, 64, v215
	v_xor_b32_e32 v56, 1, v215
	v_add_u32_e32 v59, 64, v57
	v_cmp_lt_i32_e32 vcc, v56, v59
	v_xor_b32_e32 v57, 2, v215
	v_xor_b32_e32 v58, 4, v215
	v_cndmask_b32_e32 v56, v215, v56, vcc
	v_cmp_lt_i32_e32 vcc, v57, v59
	v_lshlrev_b32_e32 v56, 2, v56
	s_nop 0
	v_cndmask_b32_e32 v57, v215, v57, vcc
	v_cmp_lt_i32_e32 vcc, v58, v59
	v_lshlrev_b32_e32 v57, 2, v57
	s_nop 0
	v_cndmask_b32_e32 v58, v215, v58, vcc
	v_cmp_lt_i32_e32 vcc, v207, v59
	v_lshlrev_b32_e32 v58, 2, v58
	s_nop 0
	v_cndmask_b32_e32 v59, v215, v207, vcc
	v_mul_f32_e32 v207, v44, v44
	v_fmac_f32_e32 v207, v40, v40
	v_fmac_f32_e32 v207, v48, v48
	v_fmac_f32_e32 v207, v52, v52
	ds_bpermute_b32 v218, v56, v207
	v_lshlrev_b32_e32 v59, 2, v59
	s_waitcnt lgkmcnt(0)
	v_add_f32_e32 v207, v207, v218
	ds_bpermute_b32 v218, v57, v207
	s_waitcnt lgkmcnt(0)
	v_add_f32_e32 v207, v207, v218
	ds_bpermute_b32 v218, v58, v207
	s_waitcnt lgkmcnt(0)
	v_add_f32_e32 v218, v207, v218
	ds_bpermute_b32 v219, v59, v218
	v_add_u32_e32 v207, s87, v96
	s_and_saveexec_b64 s[2:3], s[10:11]
	s_cbranch_execz .LBB0_818
	s_waitcnt lgkmcnt(0)
	v_add_f32_e32 v218, v218, v219
	ds_write_b32 v207, v218

; __device__ __forceinline__ void item_hgrn(const Params& p, int l, int sidx) {
;     ...
;     {
; #pragma unroll
;       for (int ks = 0; ks < 2; ++ks) {
;         bf16x8 a = *reinterpret_cast<const bf16x8*>(KTs + (16 * wid + fr) * 72 + ks * 32 + fq * 8);
; #pragma unroll
;         for (int n = 0; n < 8; ++n) {
;           bf16x8 bb = *reinterpret_cast<const bf16x8*>(VTs + (n * 16 + fr) * 72 + ks * 32 + fq * 8);
;           S[n] = __builtin_amdgcn_mfma_f32_16x16x32_bf16(a, bb, S[n], 0, 0, 0);
;         }
;       }
;       float e4[4];
; #pragma unroll
;       for (int j = 0; j < 4; ++j) e4[j] = el[16 * wid + fq * 4 + j];
; #pragma unroll
;       for (int n = 0; n < 8; ++n)
; #pragma unroll
;         for (int j = 0; j < 4; ++j) S[n][j] *= e4[j];
;     }
;     __syncthreads();
; #pragma unroll
;     for (int j = 0; j < 4; ++j) {
;       int tl = tt * 16 + fq * 4 + j;
;       if (t0 + tl < T) {
;         float ss = ssq[tl] + ssq[64 + tl];
.LBB0_824:
	s_or_b64 exec, exec, s[2:3]
	s_waitcnt lgkmcnt(0)
	ds_read_b128 v[56:59], v84 offset:34816
	ds_read_b128 v[218:221], v168 offset:53248
	v_cmp_gt_u32_e32 vcc, s86, v206
	s_waitcnt lgkmcnt(0)
	v_mfma_f32_16x16x32_bf16 v[8:11], v[56:59], v[218:221], v[8:11]
	ds_read_b128 v[218:221], v169 offset:53248
	s_waitcnt lgkmcnt(0)
	v_mfma_f32_16x16x32_bf16 v[12:15], v[56:59], v[218:221], v[12:15]
	ds_read_b128 v[218:221], v170 offset:53312
	s_waitcnt lgkmcnt(0)
	v_mfma_f32_16x16x32_bf16 v[16:19], v[56:59], v[218:221], v[16:19]
	ds_read_b128 v[218:221], v171 offset:53312
	s_waitcnt lgkmcnt(0)
	v_mfma_f32_16x16x32_bf16 v[20:23], v[56:59], v[218:221], v[20:23]
	ds_read_b128 v[218:221], v172 offset:53248
	s_waitcnt lgkmcnt(0)
	v_mfma_f32_16x16x32_bf16 v[218:221], v[56:59], v[218:221], v[24:27]
	s_nop 2
	ds_read_b128 v[24:27], v173 offset:53248
	s_waitcnt lgkmcnt(0)
	v_mfma_f32_16x16x32_bf16 v[222:225], v[56:59], v[24:27], v[28:31]
	ds_read_b128 v[24:27], v174 offset:53312
	s_waitcnt lgkmcnt(0)
	v_mfma_f32_16x16x32_bf16 v[226:229], v[56:59], v[24:27], v[32:35]
	ds_read_b128 v[24:27], v175 offset:53312
	s_waitcnt lgkmcnt(0)
	v_mfma_f32_16x16x32_bf16 v[36:39], v[56:59], v[24:27], v[36:39]
	ds_read_b128 v[230:233], v84 offset:34880
	ds_read_b128 v[24:27], v168 offset:53312
	s_waitcnt lgkmcnt(0)
	v_mfma_f32_16x16x32_bf16 v[8:11], v[230:233], v[24:27], v[8:11]
	ds_read_b128 v[24:27], v169 offset:53312
	s_waitcnt lgkmcnt(0)
	v_mfma_f32_16x16x32_bf16 v[12:15], v[230:233], v[24:27], v[12:15]
	ds_read_b128 v[24:27], v170 offset:53248
	s_waitcnt lgkmcnt(0)
	v_mfma_f32_16x16x32_bf16 v[16:19], v[230:233], v[24:27], v[16:19]
	ds_read_b128 v[24:27], v171 offset:53248
	s_waitcnt lgkmcnt(0)
	v_mfma_f32_16x16x32_bf16 v[24:27], v[230:233], v[24:27], v[20:23]
	s_nop 2
	ds_read_b128 v[20:23], v172 offset:53312
	s_waitcnt lgkmcnt(0)
	v_mfma_f32_16x16x32_bf16 v[28:31], v[230:233], v[20:23], v[218:221]
	ds_read_b128 v[20:23], v173 offset:53312
	s_waitcnt lgkmcnt(0)
	v_mfma_f32_16x16x32_bf16 v[32:35], v[230:233], v[20:23], v[222:225]
	ds_read_b128 v[20:23], v174 offset:53248
	s_waitcnt lgkmcnt(0)
	v_mfma_f32_16x16x32_bf16 v[56:59], v[230:233], v[20:23], v[226:229]
	ds_read_b128 v[20:23], v175 offset:53248
	s_waitcnt lgkmcnt(0)
	v_mfma_f32_16x16x32_bf16 v[20:23], v[230:233], v[20:23], v[36:39]
	s_nop 2
	v_add_u32_e32 v36, s88, v96
	ds_read_b128 v[36:39], v36
	s_waitcnt lgkmcnt(0)
	s_barrier
	s_and_saveexec_b64 s[28:29], vcc
	s_cbranch_execnz .LBB0_828
	s_or_b64 exec, exec, s[28:29]
	v_cmp_gt_u32_e32 vcc, s86, v201
	s_and_saveexec_b64 s[28:29], vcc
	s_cbranch_execnz .LBB0_829
